# tconv instances 1-4: two tiles per iteration with next pair prefetched (4 loads in flight)
# speedup vs baseline: 1.0165x; 1.0165x over previous
; __device__ __forceinline__ u32x4 pack8(const float* f) { u32x4 w; w.x = pk2(f[0], f[1]); w.y = pk2(f[2], f[3]); w.z = pk2(f[4], f[5]); w.w = pk2(f[6], f[7]); return w; }
; __device__ void tconv(unsigned char* smem, const float* src, int ldsrc, int col0, int N, int K, u16* dst, int ldd) {
;     float* T = (float*)smem;
;     const int tid = threadIdx.x, tilesN = N >> 6, ntile = tilesN * (K >> 6);
;     const int lr = tid >> 4, lc = (tid & 15) * 4;
;     const int sn = tid >> 3, sk = (tid & 7) * 8;
;     int tile = blockIdx.x;
;     f32x4 v0 = {0.f, 0.f, 0.f, 0.f}, v1 = {0.f, 0.f, 0.f, 0.f};
;     if (tile < ntile) { const int tn = tile % tilesN, tk = tile / tilesN; const float* s = src + (size_t)(tk * 64 + lr) * ldsrc + col0 + tn * 64 + lc;
;         v0 = __builtin_nontemporal_load((const f32x4*)s); v1 = __builtin_nontemporal_load((const f32x4*)(s + (size_t)32 * ldsrc)); }
;     for (; tile < ntile; tile += gridDim.x) {
;         const int tn = tile % tilesN, tk = tile / tilesN;
; #pragma unroll
;         for (int j = 0; j < 4; ++j) { T[lr * 65 + lc + j] = v0[j]; T[(lr + 32) * 65 + lc + j] = v1[j]; }
;         asm volatile("s_waitcnt lgkmcnt(0)" ::: "memory"); __builtin_amdgcn_s_barrier(); asm volatile("" ::: "memory");
;         const int nx = tile + gridDim.x;
;         if (nx < ntile) { const int tn2 = nx % tilesN, tk2 = nx / tilesN; const float* s = src + (size_t)(tk2 * 64 + lr) * ldsrc + col0 + tn2 * 64 + lc;
;             v0 = __builtin_nontemporal_load((const f32x4*)s); v1 = __builtin_nontemporal_load((const f32x4*)(s + (size_t)32 * ldsrc)); }
;         float f[8];
; #pragma unroll
;         for (int j = 0; j < 8; ++j) f[j] = T[(sk + j) * 65 + sn];
;         *(u32x4*)(dst + (size_t)(tn * 64 + sn) * ldd + tk * 64 + sk) = pack8(f);
;         asm volatile("s_waitcnt lgkmcnt(0)" ::: "memory"); __builtin_amdgcn_s_barrier(); asm volatile("" ::: "memory");
;     }
;     __syncthreads();
; }
_Z4mega6Params:
	s_mov_b32 s100, 0
	s_mov_b32 s70, s2
	s_mov_b64 s[16:17], s[0:1]
	s_load_dwordx2 s[88:89], s[0:1], 0x0
	s_nop 0
	s_load_dwordx16 s[0:15], s[16:17], 0x10
	s_add_u32 s68, s16, 0x160
	s_addc_u32 s69, s17, 0
	s_waitcnt lgkmcnt(0)
	v_writelane_b32 v251, s0, 0
	s_nop 1
	v_writelane_b32 v251, s1, 1
	v_writelane_b32 v251, s2, 2
	v_writelane_b32 v251, s3, 3
	v_writelane_b32 v251, s4, 4
	v_writelane_b32 v251, s5, 5
	v_writelane_b32 v251, s6, 6
	v_writelane_b32 v251, s7, 7
	v_writelane_b32 v251, s8, 8
	v_writelane_b32 v251, s9, 9
	v_writelane_b32 v251, s10, 10
	v_writelane_b32 v251, s11, 11
	v_writelane_b32 v251, s12, 12
	v_writelane_b32 v251, s13, 13
	v_writelane_b32 v251, s14, 14
	v_writelane_b32 v251, s15, 15
	s_load_dwordx16 s[72:87], s[16:17], 0x50
	s_load_dwordx4 s[64:67], s[16:17], 0x150
	s_load_dwordx16 s[0:15], s[16:17], 0x90
	s_waitcnt lgkmcnt(0)
	s_cmp_lt_i32 s66, 1
	v_writelane_b32 v251, s0, 16
	s_nop 1
	v_writelane_b32 v251, s1, 17
	v_writelane_b32 v251, s2, 18
	v_writelane_b32 v251, s3, 19
	v_writelane_b32 v251, s4, 20
	v_writelane_b32 v251, s5, 21
	v_writelane_b32 v251, s6, 22
	v_writelane_b32 v251, s7, 23
	v_writelane_b32 v251, s8, 24
	v_writelane_b32 v251, s9, 25
	v_writelane_b32 v251, s10, 26
	v_writelane_b32 v251, s11, 27
	v_writelane_b32 v251, s12, 28
	v_writelane_b32 v251, s13, 29
	v_writelane_b32 v251, s14, 30
	v_writelane_b32 v251, s15, 31
	v_writelane_b32 v251, s16, 32
	s_load_dword s62, s[16:17], 0x160
	s_cselect_b64 s[0:1], -1, 0
	s_cmp_gt_i32 s67, 0
	s_cselect_b64 s[2:3], -1, 0
	s_and_b64 s[0:1], s[0:1], s[2:3]
	s_andn2_b64 vcc, exec, s[0:1]
	v_writelane_b32 v251, s17, 33
	s_cbranch_vccnz .LBB0_25
	v_and_b32_e32 v1, 0x3ff, v0
	v_lshlrev_b32_e32 v14, 2, v1
	v_bfe_u32 v16, v0, 4, 6
	v_and_b32_e32 v2, 60, v14
	v_lshlrev_b32_e32 v15, 3, v1
	v_lshlrev_b32_e32 v10, 2, v2
	v_mul_u32_u24_e32 v2, 0x41, v16
	v_bfe_u32 v17, v0, 3, 7
	v_and_b32_e32 v19, 56, v15
	v_lshlrev_b32_e32 v2, 2, v2
	s_cmpk_gt_i32 s70, 0xfff
	v_mov_b32_e32 v11, 0
	v_add3_u32 v18, 0, v10, v2
	v_add3_u32 v20, 0, v2, v10
	v_lshl_add_u32 v21, v17, 2, 0
	v_mul_u32_u24_e32 v22, 0x104, v19
	s_cbranch_scc1 .LBB0_8
	s_waitcnt vmcnt(0) lgkmcnt(0)
	s_barrier
	v_readlane_b32 s56, v251, 32
	v_readlane_b32 s57, v251, 33
	v_and_b32_e32 v142, 0x3ff, v0
	v_lshrrev_b32_e32 v153, 4, v142
	v_and_b32_e32 v154, 15, v142
	v_lshlrev_b32_e32 v154, 4, v154
	v_lshlrev_b32_e32 v143, 15, v153
	s_load_dwordx2 s[40:41], s[56:57], 0x10
	v_add_u32_e32 v143, v143, v154
	v_mul_u32_u24_e32 v145, 0x104, v153
	v_add_u32_e32 v145, v145, v154
	v_add_u32_e32 v146, 0x2080, v145
	v_add_u32_e32 v147, 0x4100, v145
	v_add_u32_e32 v148, 0x6180, v145
	v_lshrrev_b32_e32 v153, 3, v142
	v_and_b32_e32 v154, 7, v142
	v_mul_u32_u24_e32 v149, 0x820, v154
	v_lshl_add_u32 v149, v153, 2, v149
	v_add_u32_e32 v150, 0x400, v149
	v_add_u32_e32 v151, 0x4100, v149
	v_add_u32_e32 v152, 0x4500, v149
	v_lshlrev_b32_e32 v144, 12, v153
	v_lshl_add_u32 v144, v154, 4, v144
	s_add_u32 s44, s64, 0x1c000000
	s_addc_u32 s45, s65, 0
	s_lshl_b32 s54, s62, 1
	s_mov_b32 s46, s70
	s_waitcnt lgkmcnt(0)
	s_add_u32 s42, s40, 0x100000
	s_addc_u32 s43, s41, 0
	s_add_i32 s47, s46, s62
	s_cmpk_lt_i32 s47, 0x1000
	s_cselect_b32 s47, s47, s46
	s_and_b32 s52, s46, 0x7f
	s_lshr_b32 s53, s46, 7
	s_lshl_b32 s52, s52, 8
	s_lshl_b32 s53, s53, 21
	s_add_i32 s48, s52, s53
	s_and_b32 s52, s47, 0x7f
	s_lshr_b32 s53, s47, 7
	s_lshl_b32 s52, s52, 8
	s_lshl_b32 s53, s53, 21
	s_add_i32 s49, s52, s53
	v_add_u32_e32 v153, s48, v143
	v_add_u32_e32 v172, s49, v143
	global_load_dwordx4 v[70:73], v153, s[40:41] nt
	global_load_dwordx4 v[74:77], v153, s[42:43] nt
	global_load_dwordx4 v[78:81], v172, s[40:41] nt
	global_load_dwordx4 v[82:85], v172, s[42:43] nt
	s_waitcnt vmcnt(0)
TCV1_body:
	ds_write2_b32 v145, v70, v71 offset1:1
	ds_write2_b32 v145, v72, v73 offset0:2 offset1:3
	ds_write2_b32 v146, v74, v75 offset1:1
	ds_write2_b32 v146, v76, v77 offset0:2 offset1:3
	ds_write2_b32 v147, v78, v79 offset1:1
	ds_write2_b32 v147, v80, v81 offset0:2 offset1:3
	ds_write2_b32 v148, v82, v83 offset1:1
	ds_write2_b32 v148, v84, v85 offset0:2 offset1:3
	s_and_b32 s52, s46, 0x7f
	s_lshr_b32 s53, s46, 7
	s_lshl_b32 s52, s52, 18
	s_lshl_b32 s53, s53, 7
	s_add_i32 s50, s52, s53
	s_and_b32 s52, s47, 0x7f
	s_lshr_b32 s53, s47, 7
	s_lshl_b32 s52, s52, 18
	s_lshl_b32 s53, s53, 7
	s_add_i32 s51, s52, s53
	s_waitcnt lgkmcnt(0)
	s_barrier
	s_add_i32 s46, s46, s54
	s_cmpk_lt_i32 s46, 0x1000
	s_cbranch_scc0 TCV1_noload
	s_add_i32 s47, s46, s62
	s_cmpk_lt_i32 s47, 0x1000
	s_cselect_b32 s47, s47, s46
	s_and_b32 s52, s46, 0x7f
	s_lshr_b32 s53, s46, 7
	s_lshl_b32 s52, s52, 8
	s_lshl_b32 s53, s53, 21
	s_add_i32 s48, s52, s53
	s_and_b32 s52, s47, 0x7f
	s_lshr_b32 s53, s47, 7
	s_lshl_b32 s52, s52, 8
	s_lshl_b32 s53, s53, 21
	s_add_i32 s49, s52, s53
	v_add_u32_e32 v153, s48, v143
	v_add_u32_e32 v172, s49, v143
	global_load_dwordx4 v[70:73], v153, s[40:41] nt
	global_load_dwordx4 v[74:77], v153, s[42:43] nt
	global_load_dwordx4 v[78:81], v172, s[40:41] nt
	global_load_dwordx4 v[82:85], v172, s[42:43] nt
; __device__ __forceinline__ u32x4 pack8(const float* f) { u32x4 w; w.x = pk2(f[0], f[1]); w.y = pk2(f[2], f[3]); w.z = pk2(f[4], f[5]); w.w = pk2(f[6], f[7]); return w; }
; __device__ void tconv(unsigned char* smem, const float* src, int ldsrc, int col0, int N, int K, u16* dst, int ldd) {
;     float* T = (float*)smem;
;     const int tid = threadIdx.x, tilesN = N >> 6, ntile = tilesN * (K >> 6);
;     const int lr = tid >> 4, lc = (tid & 15) * 4;
;     const int sn = tid >> 3, sk = (tid & 7) * 8;
;     int tile = blockIdx.x;
;     f32x4 v0 = {0.f, 0.f, 0.f, 0.f}, v1 = {0.f, 0.f, 0.f, 0.f};
;     if (tile < ntile) { const int tn = tile % tilesN, tk = tile / tilesN; const float* s = src + (size_t)(tk * 64 + lr) * ldsrc + col0 + tn * 64 + lc;
;         v0 = __builtin_nontemporal_load((const f32x4*)s); v1 = __builtin_nontemporal_load((const f32x4*)(s + (size_t)32 * ldsrc)); }
;     for (; tile < ntile; tile += gridDim.x) {
;         const int tn = tile % tilesN, tk = tile / tilesN;
; #pragma unroll
;         for (int j = 0; j < 4; ++j) { T[lr * 65 + lc + j] = v0[j]; T[(lr + 32) * 65 + lc + j] = v1[j]; }
;         asm volatile("s_waitcnt lgkmcnt(0)" ::: "memory"); __builtin_amdgcn_s_barrier(); asm volatile("" ::: "memory");
;         const int nx = tile + gridDim.x;
;         if (nx < ntile) { const int tn2 = nx % tilesN, tk2 = nx / tilesN; const float* s = src + (size_t)(tk2 * 64 + lr) * ldsrc + col0 + tn2 * 64 + lc;
;             v0 = __builtin_nontemporal_load((const f32x4*)s); v1 = __builtin_nontemporal_load((const f32x4*)(s + (size_t)32 * ldsrc)); }
;         float f[8];
; #pragma unroll
;         for (int j = 0; j < 8; ++j) f[j] = T[(sk + j) * 65 + sn];
;         *(u32x4*)(dst + (size_t)(tn * 64 + sn) * ldd + tk * 64 + sk) = pack8(f);
;         asm volatile("s_waitcnt lgkmcnt(0)" ::: "memory"); __builtin_amdgcn_s_barrier(); asm volatile("" ::: "memory");
;     }
;     __syncthreads();
; }
TCV1_noload:
	ds_read2_b32 v[156:157], v149 offset1:65
	ds_read2_b32 v[158:159], v149 offset0:130 offset1:195
	ds_read2_b32 v[160:161], v150 offset0:4 offset1:69
	ds_read2_b32 v[162:163], v150 offset0:134 offset1:199
	ds_read2_b32 v[164:165], v151 offset1:65
	ds_read2_b32 v[166:167], v151 offset0:130 offset1:195
	ds_read2_b32 v[168:169], v152 offset0:4 offset1:69
	ds_read2_b32 v[170:171], v152 offset0:134 offset1:199
	v_add_u32_e32 v154, s50, v144
	v_add_u32_e32 v155, s51, v144
	s_waitcnt lgkmcnt(7)
	v_cvt_pk_bf16_f32 v156, v156, v157
	s_waitcnt lgkmcnt(6)
	v_cvt_pk_bf16_f32 v157, v158, v159
	s_waitcnt lgkmcnt(5)
	v_cvt_pk_bf16_f32 v158, v160, v161
	s_waitcnt lgkmcnt(4)
	v_cvt_pk_bf16_f32 v159, v162, v163
	global_store_dwordx4 v154, v[156:159], s[44:45]
	s_waitcnt lgkmcnt(3)
	v_cvt_pk_bf16_f32 v164, v164, v165
	s_waitcnt lgkmcnt(2)
	v_cvt_pk_bf16_f32 v165, v166, v167
	s_waitcnt lgkmcnt(1)
	v_cvt_pk_bf16_f32 v166, v168, v169
	s_waitcnt lgkmcnt(0)
	v_cvt_pk_bf16_f32 v167, v170, v171
	global_store_dwordx4 v155, v[164:167], s[44:45]
	s_barrier
	s_cmpk_lt_i32 s46, 0x1000
	s_waitcnt vmcnt(2)
	s_cbranch_scc1 TCV1_body
.LBB0_8:
	s_cmpk_gt_i32 s70, 0x7ff
	s_waitcnt lgkmcnt(0)
	s_barrier
	s_cbranch_scc1 .LBB0_15
	s_waitcnt vmcnt(0) lgkmcnt(0)
	s_barrier
	v_readlane_b32 s56, v251, 32
	v_readlane_b32 s57, v251, 33
	v_and_b32_e32 v142, 0x3ff, v0
	v_lshrrev_b32_e32 v153, 4, v142
	v_and_b32_e32 v154, 15, v142
	v_lshlrev_b32_e32 v154, 4, v154
	v_lshlrev_b32_e32 v143, 13, v153
	s_load_dwordx2 s[40:41], s[56:57], 0xa8
	v_add_u32_e32 v143, v143, v154
	v_mul_u32_u24_e32 v145, 0x104, v153
	v_add_u32_e32 v145, v145, v154
	v_add_u32_e32 v146, 0x2080, v145
	v_add_u32_e32 v147, 0x4100, v145
	v_add_u32_e32 v148, 0x6180, v145
	v_lshrrev_b32_e32 v153, 3, v142
	v_and_b32_e32 v154, 7, v142
	v_mul_u32_u24_e32 v149, 0x820, v154
	v_lshl_add_u32 v149, v153, 2, v149
	v_add_u32_e32 v150, 0x400, v149
	v_add_u32_e32 v151, 0x4100, v149
	v_add_u32_e32 v152, 0x4500, v149
	v_lshlrev_b32_e32 v144, 13, v153
	v_lshl_add_u32 v144, v154, 4, v144
	s_add_u32 s44, s64, 0x1e000000
	s_addc_u32 s45, s65, 0
	s_lshl_b32 s54, s62, 1
	s_mov_b32 s46, s70
	s_waitcnt lgkmcnt(0)
	s_add_u32 s42, s40, 0x40000
	s_addc_u32 s43, s41, 0
	s_add_i32 s47, s46, s62
	s_cmpk_lt_i32 s47, 0x800
	s_cselect_b32 s47, s47, s46
	s_and_b32 s52, s46, 0x1f
	s_lshr_b32 s53, s46, 5
	s_lshl_b32 s52, s52, 8
	s_lshl_b32 s53, s53, 19
	s_add_i32 s48, s52, s53
	s_and_b32 s52, s47, 0x1f
	s_lshr_b32 s53, s47, 5
	s_lshl_b32 s52, s52, 8
	s_lshl_b32 s53, s53, 19
	s_add_i32 s49, s52, s53
	v_add_u32_e32 v153, s48, v143
	v_add_u32_e32 v172, s49, v143
	global_load_dwordx4 v[70:73], v153, s[40:41] nt
	global_load_dwordx4 v[74:77], v153, s[42:43] nt
	global_load_dwordx4 v[78:81], v172, s[40:41] nt
	global_load_dwordx4 v[82:85], v172, s[42:43] nt
	s_waitcnt vmcnt(0)
TCV2_body:
	ds_write2_b32 v145, v70, v71 offset1:1
	ds_write2_b32 v145, v72, v73 offset0:2 offset1:3
	ds_write2_b32 v146, v74, v75 offset1:1
	ds_write2_b32 v146, v76, v77 offset0:2 offset1:3
	ds_write2_b32 v147, v78, v79 offset1:1
	ds_write2_b32 v147, v80, v81 offset0:2 offset1:3
	ds_write2_b32 v148, v82, v83 offset1:1
	ds_write2_b32 v148, v84, v85 offset0:2 offset1:3
	s_and_b32 s52, s46, 0x1f
	s_lshr_b32 s53, s46, 5
	s_lshl_b32 s52, s52, 19
	s_lshl_b32 s53, s53, 7
	s_add_i32 s50, s52, s53
	s_and_b32 s52, s47, 0x1f
	s_lshr_b32 s53, s47, 5
	s_lshl_b32 s52, s52, 19
	s_lshl_b32 s53, s53, 7
	s_add_i32 s51, s52, s53
	s_waitcnt lgkmcnt(0)
	s_barrier
	s_add_i32 s46, s46, s54
	s_cmpk_lt_i32 s46, 0x800
	s_cbranch_scc0 TCV2_noload
	s_add_i32 s47, s46, s62
	s_cmpk_lt_i32 s47, 0x800
	s_cselect_b32 s47, s47, s46
	s_and_b32 s52, s46, 0x1f
	s_lshr_b32 s53, s46, 5
	s_lshl_b32 s52, s52, 8
	s_lshl_b32 s53, s53, 19
	s_add_i32 s48, s52, s53
	s_and_b32 s52, s47, 0x1f
	s_lshr_b32 s53, s47, 5
	s_lshl_b32 s52, s52, 8
	s_lshl_b32 s53, s53, 19
	s_add_i32 s49, s52, s53
	v_add_u32_e32 v153, s48, v143
	v_add_u32_e32 v172, s49, v143
	global_load_dwordx4 v[70:73], v153, s[40:41] nt
	global_load_dwordx4 v[74:77], v153, s[42:43] nt
	global_load_dwordx4 v[78:81], v172, s[40:41] nt
	global_load_dwordx4 v[82:85], v172, s[42:43] nt
TCV2_noload:
	ds_read2_b32 v[156:157], v149 offset1:65
	ds_read2_b32 v[158:159], v149 offset0:130 offset1:195
	ds_read2_b32 v[160:161], v150 offset0:4 offset1:69
	ds_read2_b32 v[162:163], v150 offset0:134 offset1:199
	ds_read2_b32 v[164:165], v151 offset1:65
	ds_read2_b32 v[166:167], v151 offset0:130 offset1:195
	ds_read2_b32 v[168:169], v152 offset0:4 offset1:69
	ds_read2_b32 v[170:171], v152 offset0:134 offset1:199
	v_add_u32_e32 v154, s50, v144
	v_add_u32_e32 v155, s51, v144
	s_waitcnt lgkmcnt(7)
	v_cvt_pk_bf16_f32 v156, v156, v157
	s_waitcnt lgkmcnt(6)
	v_cvt_pk_bf16_f32 v157, v158, v159
	s_waitcnt lgkmcnt(5)
	v_cvt_pk_bf16_f32 v158, v160, v161
	s_waitcnt lgkmcnt(4)
	v_cvt_pk_bf16_f32 v159, v162, v163
	global_store_dwordx4 v154, v[156:159], s[44:45]
	s_waitcnt lgkmcnt(3)
	v_cvt_pk_bf16_f32 v164, v164, v165
	s_waitcnt lgkmcnt(2)
	v_cvt_pk_bf16_f32 v165, v166, v167
	s_waitcnt lgkmcnt(1)
	v_cvt_pk_bf16_f32 v166, v168, v169
	s_waitcnt lgkmcnt(0)
	v_cvt_pk_bf16_f32 v167, v170, v171
	global_store_dwordx4 v155, v[164:167], s[44:45]
	s_barrier
	s_cmpk_lt_i32 s46, 0x800
	s_waitcnt vmcnt(2)
	s_cbranch_scc1 TCV2_body

; __device__ __forceinline__ u32x4 pack8(const float* f) { u32x4 w; w.x = pk2(f[0], f[1]); w.y = pk2(f[2], f[3]); w.z = pk2(f[4], f[5]); w.w = pk2(f[6], f[7]); return w; }
; __device__ void tconv(unsigned char* smem, const float* src, int ldsrc, int col0, int N, int K, u16* dst, int ldd) {
;     float* T = (float*)smem;
;     const int tid = threadIdx.x, tilesN = N >> 6, ntile = tilesN * (K >> 6);
;     const int lr = tid >> 4, lc = (tid & 15) * 4;
;     const int sn = tid >> 3, sk = (tid & 7) * 8;
;     int tile = blockIdx.x;
;     f32x4 v0 = {0.f, 0.f, 0.f, 0.f}, v1 = {0.f, 0.f, 0.f, 0.f};
;     if (tile < ntile) { const int tn = tile % tilesN, tk = tile / tilesN; const float* s = src + (size_t)(tk * 64 + lr) * ldsrc + col0 + tn * 64 + lc;
;         v0 = __builtin_nontemporal_load((const f32x4*)s); v1 = __builtin_nontemporal_load((const f32x4*)(s + (size_t)32 * ldsrc)); }
;     for (; tile < ntile; tile += gridDim.x) {
;         const int tn = tile % tilesN, tk = tile / tilesN;
; #pragma unroll
;         for (int j = 0; j < 4; ++j) { T[lr * 65 + lc + j] = v0[j]; T[(lr + 32) * 65 + lc + j] = v1[j]; }
;         asm volatile("s_waitcnt lgkmcnt(0)" ::: "memory"); __builtin_amdgcn_s_barrier(); asm volatile("" ::: "memory");
;         const int nx = tile + gridDim.x;
;         if (nx < ntile) { const int tn2 = nx % tilesN, tk2 = nx / tilesN; const float* s = src + (size_t)(tk2 * 64 + lr) * ldsrc + col0 + tn2 * 64 + lc;
;             v0 = __builtin_nontemporal_load((const f32x4*)s); v1 = __builtin_nontemporal_load((const f32x4*)(s + (size_t)32 * ldsrc)); }
;         float f[8];
; #pragma unroll
;         for (int j = 0; j < 8; ++j) f[j] = T[(sk + j) * 65 + sn];
;         *(u32x4*)(dst + (size_t)(tn * 64 + sn) * ldd + tk * 64 + sk) = pack8(f);
;         asm volatile("s_waitcnt lgkmcnt(0)" ::: "memory"); __builtin_amdgcn_s_barrier(); asm volatile("" ::: "memory");
;     }
;     __syncthreads();
; }
.LBB0_617:
	s_cmpk_gt_i32 s70, 0xfff
	s_cbranch_scc1 .LBB0_624
	s_waitcnt vmcnt(0) lgkmcnt(0)
	s_barrier
	v_readlane_b32 s56, v251, 32
	v_readlane_b32 s57, v251, 33
	v_and_b32_e32 v142, 0x3ff, v0
	v_lshrrev_b32_e32 v153, 4, v142
	v_and_b32_e32 v154, 15, v142
	v_lshlrev_b32_e32 v154, 4, v154
	v_lshlrev_b32_e32 v143, 16, v153
	s_load_dwordx2 s[40:41], s[56:57], 0xc0
	v_add_u32_e32 v143, v143, v154
	v_mul_u32_u24_e32 v145, 0x104, v153
	v_add_u32_e32 v145, v145, v154
	v_add_u32_e32 v146, 0x2080, v145
	v_add_u32_e32 v147, 0x4100, v145
	v_add_u32_e32 v148, 0x6180, v145
	v_lshrrev_b32_e32 v153, 3, v142
	v_and_b32_e32 v154, 7, v142
	v_mul_u32_u24_e32 v149, 0x820, v154
	v_lshl_add_u32 v149, v153, 2, v149
	v_add_u32_e32 v150, 0x400, v149
	v_add_u32_e32 v151, 0x4100, v149
	v_add_u32_e32 v152, 0x4500, v149
	v_lshlrev_b32_e32 v144, 12, v153
	v_lshl_add_u32 v144, v154, 4, v144
	s_add_u32 s44, s64, 0x1c000000
	s_addc_u32 s45, s65, 0
	s_lshl_b32 s54, s62, 1
	s_mov_b32 s46, s70
	s_waitcnt lgkmcnt(0)
	s_add_u32 s42, s40, 0x200000
	s_addc_u32 s43, s41, 0
	s_add_i32 s47, s46, s62
	s_cmpk_lt_i32 s47, 0x1000
	s_cselect_b32 s47, s47, s46
	s_and_b32 s52, s46, 0x7f
	s_lshr_b32 s53, s46, 7
	s_lshl_b32 s52, s52, 8
	s_lshl_b32 s53, s53, 22
	s_add_i32 s48, s52, s53
	s_and_b32 s52, s47, 0x7f
	s_lshr_b32 s53, s47, 7
	s_lshl_b32 s52, s52, 8
	s_lshl_b32 s53, s53, 22
	s_add_i32 s49, s52, s53
	v_add_u32_e32 v153, s48, v143
	v_add_u32_e32 v172, s49, v143
	global_load_dwordx4 v[70:73], v153, s[40:41] nt
	global_load_dwordx4 v[74:77], v153, s[42:43] nt
	global_load_dwordx4 v[78:81], v172, s[40:41] nt
	global_load_dwordx4 v[82:85], v172, s[42:43] nt
	s_waitcnt vmcnt(0)
TCV3_body:
	ds_write2_b32 v145, v70, v71 offset1:1
	ds_write2_b32 v145, v72, v73 offset0:2 offset1:3
	ds_write2_b32 v146, v74, v75 offset1:1
	ds_write2_b32 v146, v76, v77 offset0:2 offset1:3
	ds_write2_b32 v147, v78, v79 offset1:1
	ds_write2_b32 v147, v80, v81 offset0:2 offset1:3
	ds_write2_b32 v148, v82, v83 offset1:1
	ds_write2_b32 v148, v84, v85 offset0:2 offset1:3
	s_and_b32 s52, s46, 0x7f
	s_lshr_b32 s53, s46, 7
	s_lshl_b32 s52, s52, 18
	s_lshl_b32 s53, s53, 7
	s_add_i32 s50, s52, s53
	s_and_b32 s52, s47, 0x7f
	s_lshr_b32 s53, s47, 7
	s_lshl_b32 s52, s52, 18
	s_lshl_b32 s53, s53, 7
	s_add_i32 s51, s52, s53
	s_waitcnt lgkmcnt(0)
	s_barrier
	s_add_i32 s46, s46, s54
	s_cmpk_lt_i32 s46, 0x1000
	s_cbranch_scc0 TCV3_noload
	s_add_i32 s47, s46, s62
	s_cmpk_lt_i32 s47, 0x1000
	s_cselect_b32 s47, s47, s46
	s_and_b32 s52, s46, 0x7f
	s_lshr_b32 s53, s46, 7
	s_lshl_b32 s52, s52, 8
	s_lshl_b32 s53, s53, 22
	s_add_i32 s48, s52, s53
	s_and_b32 s52, s47, 0x7f
	s_lshr_b32 s53, s47, 7
	s_lshl_b32 s52, s52, 8
	s_lshl_b32 s53, s53, 22
	s_add_i32 s49, s52, s53
	v_add_u32_e32 v153, s48, v143
	v_add_u32_e32 v172, s49, v143
	global_load_dwordx4 v[70:73], v153, s[40:41] nt
	global_load_dwordx4 v[74:77], v153, s[42:43] nt
	global_load_dwordx4 v[78:81], v172, s[40:41] nt
	global_load_dwordx4 v[82:85], v172, s[42:43] nt
TCV3_noload:
	ds_read2_b32 v[156:157], v149 offset1:65
	ds_read2_b32 v[158:159], v149 offset0:130 offset1:195
	ds_read2_b32 v[160:161], v150 offset0:4 offset1:69
	ds_read2_b32 v[162:163], v150 offset0:134 offset1:199
	ds_read2_b32 v[164:165], v151 offset1:65
	ds_read2_b32 v[166:167], v151 offset0:130 offset1:195
	ds_read2_b32 v[168:169], v152 offset0:4 offset1:69
	ds_read2_b32 v[170:171], v152 offset0:134 offset1:199
	v_add_u32_e32 v154, s50, v144
	v_add_u32_e32 v155, s51, v144
	s_waitcnt lgkmcnt(7)
	v_cvt_pk_bf16_f32 v156, v156, v157
	s_waitcnt lgkmcnt(6)
	v_cvt_pk_bf16_f32 v157, v158, v159
	s_waitcnt lgkmcnt(5)
	v_cvt_pk_bf16_f32 v158, v160, v161
	s_waitcnt lgkmcnt(4)
	v_cvt_pk_bf16_f32 v159, v162, v163
	global_store_dwordx4 v154, v[156:159], s[44:45]
	s_waitcnt lgkmcnt(3)
	v_cvt_pk_bf16_f32 v164, v164, v165
	s_waitcnt lgkmcnt(2)
	v_cvt_pk_bf16_f32 v165, v166, v167
	s_waitcnt lgkmcnt(1)
	v_cvt_pk_bf16_f32 v166, v168, v169
	s_waitcnt lgkmcnt(0)
	v_cvt_pk_bf16_f32 v167, v170, v171
	global_store_dwordx4 v155, v[164:167], s[44:45]
	s_barrier
	s_cmpk_lt_i32 s46, 0x1000
	s_waitcnt vmcnt(2)
	s_cbranch_scc1 TCV3_body

; __device__ __forceinline__ u32x4 pack8(const float* f) { u32x4 w; w.x = pk2(f[0], f[1]); w.y = pk2(f[2], f[3]); w.z = pk2(f[4], f[5]); w.w = pk2(f[6], f[7]); return w; }
; __device__ void tconv(unsigned char* smem, const float* src, int ldsrc, int col0, int N, int K, u16* dst, int ldd) {
;     float* T = (float*)smem;
;     const int tid = threadIdx.x, tilesN = N >> 6, ntile = tilesN * (K >> 6);
;     const int lr = tid >> 4, lc = (tid & 15) * 4;
;     const int sn = tid >> 3, sk = (tid & 7) * 8;
;     int tile = blockIdx.x;
;     f32x4 v0 = {0.f, 0.f, 0.f, 0.f}, v1 = {0.f, 0.f, 0.f, 0.f};
;     if (tile < ntile) { const int tn = tile % tilesN, tk = tile / tilesN; const float* s = src + (size_t)(tk * 64 + lr) * ldsrc + col0 + tn * 64 + lc;
;         v0 = __builtin_nontemporal_load((const f32x4*)s); v1 = __builtin_nontemporal_load((const f32x4*)(s + (size_t)32 * ldsrc)); }
;     for (; tile < ntile; tile += gridDim.x) {
;         const int tn = tile % tilesN, tk = tile / tilesN;
; #pragma unroll
;         for (int j = 0; j < 4; ++j) { T[lr * 65 + lc + j] = v0[j]; T[(lr + 32) * 65 + lc + j] = v1[j]; }
;         asm volatile("s_waitcnt lgkmcnt(0)" ::: "memory"); __builtin_amdgcn_s_barrier(); asm volatile("" ::: "memory");
;         const int nx = tile + gridDim.x;
;         if (nx < ntile) { const int tn2 = nx % tilesN, tk2 = nx / tilesN; const float* s = src + (size_t)(tk2 * 64 + lr) * ldsrc + col0 + tn2 * 64 + lc;
;             v0 = __builtin_nontemporal_load((const f32x4*)s); v1 = __builtin_nontemporal_load((const f32x4*)(s + (size_t)32 * ldsrc)); }
;         float f[8];
; #pragma unroll
;         for (int j = 0; j < 8; ++j) f[j] = T[(sk + j) * 65 + sn];
;         *(u32x4*)(dst + (size_t)(tn * 64 + sn) * ldd + tk * 64 + sk) = pack8(f);
;         asm volatile("s_waitcnt lgkmcnt(0)" ::: "memory"); __builtin_amdgcn_s_barrier(); asm volatile("" ::: "memory");
;     }
;     __syncthreads();
; }
.LBB0_674:
	s_or_b64 exec, exec, s[2:3]
	s_cmpk_gt_i32 s70, 0x7ff
	s_cbranch_scc1 .LBB0_681
	s_waitcnt vmcnt(0) lgkmcnt(0)
	s_barrier
	v_readlane_b32 s56, v251, 32
	v_readlane_b32 s57, v251, 33
	v_and_b32_e32 v142, 0x3ff, v0
	v_lshrrev_b32_e32 v153, 4, v142
	v_and_b32_e32 v154, 15, v142
	v_lshlrev_b32_e32 v154, 4, v154
	v_lshlrev_b32_e32 v143, 16, v153
	s_load_dwordx2 s[40:41], s[56:57], 0xc0
	v_add_u32_e32 v143, v143, v154
	v_mul_u32_u24_e32 v145, 0x104, v153
	v_add_u32_e32 v145, v145, v154
	v_add_u32_e32 v146, 0x2080, v145
	v_add_u32_e32 v147, 0x4100, v145
	v_add_u32_e32 v148, 0x6180, v145
	v_lshrrev_b32_e32 v153, 3, v142
	v_and_b32_e32 v154, 7, v142
	v_mul_u32_u24_e32 v149, 0x820, v154
	v_lshl_add_u32 v149, v153, 2, v149
	v_add_u32_e32 v150, 0x400, v149
	v_add_u32_e32 v151, 0x4100, v149
	v_add_u32_e32 v152, 0x4500, v149
	v_lshlrev_b32_e32 v144, 12, v153
	v_lshl_add_u32 v144, v154, 4, v144
	s_add_u32 s44, s64, 0x1e000000
	s_addc_u32 s45, s65, 0
	s_lshl_b32 s54, s62, 1
	s_mov_b32 s46, s70
	s_waitcnt lgkmcnt(0)
	s_add_u32 s40, s40, 0x8000
	s_addc_u32 s41, s41, 0
	s_add_u32 s42, s40, 0x200000
	s_addc_u32 s43, s41, 0
	s_add_i32 s47, s46, s62
	s_cmpk_lt_i32 s47, 0x800
	s_cselect_b32 s47, s47, s46
	s_and_b32 s52, s46, 0x3f
	s_lshr_b32 s53, s46, 6
	s_lshl_b32 s52, s52, 8
	s_lshl_b32 s53, s53, 22
	s_add_i32 s48, s52, s53
	s_and_b32 s52, s47, 0x3f
	s_lshr_b32 s53, s47, 6
	s_lshl_b32 s52, s52, 8
	s_lshl_b32 s53, s53, 22
	s_add_i32 s49, s52, s53
	v_add_u32_e32 v153, s48, v143
	v_add_u32_e32 v172, s49, v143
	global_load_dwordx4 v[70:73], v153, s[40:41] nt
	global_load_dwordx4 v[74:77], v153, s[42:43] nt
	global_load_dwordx4 v[78:81], v172, s[40:41] nt
	global_load_dwordx4 v[82:85], v172, s[42:43] nt
	s_waitcnt vmcnt(0)
TCV4_body:
	ds_write2_b32 v145, v70, v71 offset1:1
	ds_write2_b32 v145, v72, v73 offset0:2 offset1:3
	ds_write2_b32 v146, v74, v75 offset1:1
	ds_write2_b32 v146, v76, v77 offset0:2 offset1:3
	ds_write2_b32 v147, v78, v79 offset1:1
	ds_write2_b32 v147, v80, v81 offset0:2 offset1:3
	ds_write2_b32 v148, v82, v83 offset1:1
	ds_write2_b32 v148, v84, v85 offset0:2 offset1:3
	s_and_b32 s52, s46, 0x3f
	s_lshr_b32 s53, s46, 6
	s_lshl_b32 s52, s52, 18
	s_lshl_b32 s53, s53, 7
	s_add_i32 s50, s52, s53
	s_and_b32 s52, s47, 0x3f
	s_lshr_b32 s53, s47, 6
	s_lshl_b32 s52, s52, 18
	s_lshl_b32 s53, s53, 7
	s_add_i32 s51, s52, s53
	s_waitcnt lgkmcnt(0)
	s_barrier
	s_add_i32 s46, s46, s54
	s_cmpk_lt_i32 s46, 0x800
	s_cbranch_scc0 TCV4_noload
	s_add_i32 s47, s46, s62
	s_cmpk_lt_i32 s47, 0x800
	s_cselect_b32 s47, s47, s46
	s_and_b32 s52, s46, 0x3f
	s_lshr_b32 s53, s46, 6
	s_lshl_b32 s52, s52, 8
	s_lshl_b32 s53, s53, 22
	s_add_i32 s48, s52, s53
	s_and_b32 s52, s47, 0x3f
	s_lshr_b32 s53, s47, 6
	s_lshl_b32 s52, s52, 8
	s_lshl_b32 s53, s53, 22
	s_add_i32 s49, s52, s53
	v_add_u32_e32 v153, s48, v143
	v_add_u32_e32 v172, s49, v143
	global_load_dwordx4 v[70:73], v153, s[40:41] nt
	global_load_dwordx4 v[74:77], v153, s[42:43] nt
	global_load_dwordx4 v[78:81], v172, s[40:41] nt
	global_load_dwordx4 v[82:85], v172, s[42:43] nt
TCV4_noload:
	ds_read2_b32 v[156:157], v149 offset1:65
	ds_read2_b32 v[158:159], v149 offset0:130 offset1:195
	ds_read2_b32 v[160:161], v150 offset0:4 offset1:69
	ds_read2_b32 v[162:163], v150 offset0:134 offset1:199
	ds_read2_b32 v[164:165], v151 offset1:65
	ds_read2_b32 v[166:167], v151 offset0:130 offset1:195
	ds_read2_b32 v[168:169], v152 offset0:4 offset1:69
	ds_read2_b32 v[170:171], v152 offset0:134 offset1:199
	v_add_u32_e32 v154, s50, v144
	v_add_u32_e32 v155, s51, v144
	s_waitcnt lgkmcnt(7)
	v_cvt_pk_bf16_f32 v156, v156, v157
	s_waitcnt lgkmcnt(6)
	v_cvt_pk_bf16_f32 v157, v158, v159
	s_waitcnt lgkmcnt(5)
	v_cvt_pk_bf16_f32 v158, v160, v161
	s_waitcnt lgkmcnt(4)
	v_cvt_pk_bf16_f32 v159, v162, v163
	global_store_dwordx4 v154, v[156:159], s[44:45]
	s_waitcnt lgkmcnt(3)
	v_cvt_pk_bf16_f32 v164, v164, v165
	s_waitcnt lgkmcnt(2)
	v_cvt_pk_bf16_f32 v165, v166, v167
	s_waitcnt lgkmcnt(1)
	v_cvt_pk_bf16_f32 v166, v168, v169
	s_waitcnt lgkmcnt(0)
	v_cvt_pk_bf16_f32 v167, v170, v171
	global_store_dwordx4 v155, v[164:167], s[44:45]
	s_barrier
	s_cmpk_lt_i32 s46, 0x800
	s_waitcnt vmcnt(2)
	s_cbranch_scc1 TCV4_body
